# latent-attention items: none on the latent scans' CU-partner workgroups; workgroups 128..255 and 384..511 take two items each
# speedup vs baseline: 1.0147x; 1.0010x over previous
.LBB0_224:
	v_writelane_b32 v224, s38, 36
	v_readlane_b32 s2, v226, 6
	v_readlane_b32 s3, v226, 7
	v_writelane_b32 v224, s39, 37
	s_and_b64 vcc, exec, s[2:3]
	v_readlane_b32 s54, v224, 28
	s_mov_b64 s[74:75], 0x1200
	v_readlane_b32 s55, v224, 29
	s_cbranch_vccz .LBB0_275
	v_readlane_b32 s2, v226, 8
	v_readlane_b32 s3, v226, 9
	v_readlane_b32 s64, v225, 60
	s_mov_b32 s72, 0x1ffffc0
	s_andn2_b64 vcc, exec, s[2:3]
	v_readlane_b32 s65, v225, 61
	s_mov_b32 s67, 0x8000
	v_readlane_b32 s28, v224, 36
	v_readlane_b32 s29, v224, 37
	s_cbranch_vccnz .LBB0_240
	v_readlane_b32 s2, v224, 34
	v_readlane_b32 s3, v224, 35
	s_load_dwordx4 s[48:51], s[2:3], 0x170
	s_load_dwordx8 s[40:47], s[2:3], 0x150
	s_lshl_b32 s16, s28, 3
	v_readlane_b32 s2, v225, 58
	v_readlane_b32 s3, v225, 59
	s_waitcnt lgkmcnt(0)
	s_add_u32 s6, s50, 0x120030
	s_addc_u32 s7, s51, 0
	s_add_u32 s8, s48, 0x81040
	s_addc_u32 s9, s49, 0
	s_add_u32 s12, s40, 0x1040
	s_addc_u32 s13, s41, 0
	v_readlane_b32 s50, v224, 3
	s_nop 0
	s_cmpk_lt_u32 s50, 0x80
	s_cbranch_scc1 .LBB0_240
	s_add_i32 s100, s50, 0xffffff80
	s_cmpk_lt_u32 s50, 0x100
	s_cselect_b32 s50, s100, s50

.Lat_la_next:
	s_sub_u32 s15, s15, 1
	s_cmp_lg_u32 s15, 0
	s_cbranch_scc1 .Lat_la_tile
	v_readlane_b32 s100, v224, 34
	v_readlane_b32 s101, v224, 35
	v_mov_b32_e32 v125, v123
	s_load_dwordx2 s[20:21], s[100:101], 0x160
	s_nop 0
	v_permlane32_swap_b32_e32 v125, v123
	v_add_f32_e32 v123, v123, v125
	v_rcp_f32_e32 v128, v123
	v_readfirstlane_b32 s51, v131
	s_and_b32 s2, s50, 1
	s_lshr_b32 s51, s51, 6
	s_lshl_b32 s2, s2, 2
	s_add_i32 s2, s2, s51
	s_lshl_b32 s2, s2, 7
	s_bfe_u32 s3, s50, 0x60001
	s_lshr_b32 s14, s50, 7
	s_lshl_b32 s14, s14, 11
	s_addk_i32 s14, 0x1000
	s_lshl_b32 s3, s3, 5
	s_add_i32 s3, s3, s14
	v_and_b32_e32 v0, 31, v131
	v_add_u32_e32 v0, s3, v0
	v_lshlrev_b32_e32 v0, 11, v0
	v_bfe_u32 v134, v131, 5, 1
	v_lshl_add_u32 v0, v134, 3, v0
	v_add_u32_e32 v0, s2, v0
	s_nop 8
	v_pk_mul_f32 v[18:19], v[18:19], v[128:129] op_sel_hi:[1,0]
	v_pk_mul_f32 v[34:35], v[34:35], v[128:129] op_sel_hi:[1,0]
	v_pk_mul_f32 v[20:21], v[20:21], v[128:129] op_sel_hi:[1,0]
	v_pk_mul_f32 v[36:37], v[36:37], v[128:129] op_sel_hi:[1,0]
	v_pk_mul_f32 v[22:23], v[22:23], v[128:129] op_sel_hi:[1,0]
	v_pk_mul_f32 v[38:39], v[38:39], v[128:129] op_sel_hi:[1,0]
	v_pk_mul_f32 v[24:25], v[24:25], v[128:129] op_sel_hi:[1,0]
	v_pk_mul_f32 v[40:41], v[40:41], v[128:129] op_sel_hi:[1,0]
	v_pk_mul_f32 v[26:27], v[26:27], v[128:129] op_sel_hi:[1,0]
	v_pk_mul_f32 v[42:43], v[42:43], v[128:129] op_sel_hi:[1,0]
	v_pk_mul_f32 v[28:29], v[28:29], v[128:129] op_sel_hi:[1,0]
	v_pk_mul_f32 v[44:45], v[44:45], v[128:129] op_sel_hi:[1,0]
	v_pk_mul_f32 v[30:31], v[30:31], v[128:129] op_sel_hi:[1,0]
	v_pk_mul_f32 v[46:47], v[46:47], v[128:129] op_sel_hi:[1,0]
	v_pk_mul_f32 v[32:33], v[32:33], v[128:129] op_sel_hi:[1,0]
	v_pk_mul_f32 v[48:49], v[48:49], v[128:129] op_sel_hi:[1,0]
	v_cvt_pk_f16_f32 v50, v18, v19
	v_cvt_pk_f16_f32 v58, v34, v35
	v_cvt_pk_f16_f32 v51, v20, v21
	v_cvt_pk_f16_f32 v59, v36, v37
	v_cvt_pk_f16_f32 v52, v22, v23
	v_cvt_pk_f16_f32 v60, v38, v39
	v_cvt_pk_f16_f32 v53, v24, v25
	v_cvt_pk_f16_f32 v61, v40, v41
	v_cvt_pk_f16_f32 v54, v26, v27
	v_cvt_pk_f16_f32 v62, v42, v43
	v_cvt_pk_f16_f32 v55, v28, v29
	v_cvt_pk_f16_f32 v63, v44, v45
	v_cvt_pk_f16_f32 v56, v30, v31
	v_cvt_pk_f16_f32 v64, v46, v47
	v_cvt_pk_f16_f32 v57, v32, v33
	v_cvt_pk_f16_f32 v65, v48, v49
	s_waitcnt lgkmcnt(0)
	global_store_dwordx2 v0, v[50:51], s[20:21] offset:0
	global_store_dwordx2 v0, v[58:59], s[20:21] offset:64
	global_store_dwordx2 v0, v[52:53], s[20:21] offset:16
	global_store_dwordx2 v0, v[60:61], s[20:21] offset:80
	global_store_dwordx2 v0, v[54:55], s[20:21] offset:32
	global_store_dwordx2 v0, v[62:63], s[20:21] offset:96
	global_store_dwordx2 v0, v[56:57], s[20:21] offset:48
	global_store_dwordx2 v0, v[64:65], s[20:21] offset:112
	s_waitcnt vmcnt(0)
	s_addk_i32 s50, 0x80
	s_bitcmp1_b32 s50, 7
	s_cbranch_scc1 .LBB0_227
